# res1 micro-tile tail: 22 serialized load-wait-mfma steps replaced by 11-deep load pipeline with counted vmcnt
# speedup vs baseline: 1.0064x; 1.0021x over previous
; #define MFMA(a, b, c) __builtin_amdgcn_mfma_f32_32x32x16_bf16((a), (b), (c), 0, 0, 0)
; DI void micro_partial(f32x16& acc, const u16* A, int lda, const u16* Wt, int ldw, int K, int row0, int n0, int w, int r, int h) {
;   const int kb = w * (K >> 3), n16 = K >> 7;
;   const u16* ap = A + (size_t)(row0 + r) * lda + kb + h * 8;
;   const u16* bp = Wt + (size_t)(n0 + r) * ldw + kb + h * 8;
; #pragma unroll 4
;   for (int k = 0; k < n16; ++k) {
;     const bf16x8 a = *(const bf16x8*)(ap + k * 16);
;     const bf16x8 b = *(const bf16x8*)(bp + k * 16);
;     acc = MFMA(a, b, acc);
;   }
; }
; DI void phase_res(const Params& p, int l, int mode, unsigned char* smem) {
;     ...
;     for (int mtile = blockIdx.x; mtile < 256; mtile += gridDim.x) {
;       const int row0 = TOKP + (mtile >> 5) * 32, n0 = (mtile & 31) * 32;
;       f32x16 pa;
;       zero16(pa);
;       micro_partial(pa, Ab, K, Wb, K, K, row0, n0, w, r, h);
.LBB0_883:
	s_and_b32 s2, s1, 0xffffffe0
	s_add_i32 s3, s2, 0x10000
	s_and_b32 s6, s0, 0x3e0
	v_or_b32_e32 v0, s3, v24
	v_or_b32_e32 v40, s6, v24
	v_mad_i64_i32 v[22:23], s[4:5], v0, s10, v[16:17]
	v_mul_u32_u24_e32 v0, 0xb00, v40
	v_lshlrev_b32_e32 v178, 1, v0
	v_lshl_add_u64 v[20:21], v[18:19], 0, v[178:179]
	global_load_dwordx4 v[44:47], v[22:23], off
	global_load_dwordx4 v[48:51], v[20:21], off
	global_load_dwordx4 v[52:55], v[22:23], off offset:32
	global_load_dwordx4 v[56:59], v[20:21], off offset:32
	global_load_dwordx4 v[60:63], v[22:23], off offset:64
	global_load_dwordx4 v[64:67], v[20:21], off offset:64
	global_load_dwordx4 v[68:71], v[22:23], off offset:96
	global_load_dwordx4 v[72:75], v[20:21], off offset:96
	global_load_dwordx4 v[76:79], v[22:23], off offset:128
	global_load_dwordx4 v[80:83], v[20:21], off offset:128
	global_load_dwordx4 v[84:87], v[22:23], off offset:160
	global_load_dwordx4 v[88:91], v[20:21], off offset:160
	global_load_dwordx4 v[92:95], v[22:23], off offset:192
	global_load_dwordx4 v[96:99], v[20:21], off offset:192
	global_load_dwordx4 v[100:103], v[22:23], off offset:224
	global_load_dwordx4 v[104:107], v[20:21], off offset:224
	global_load_dwordx4 v[108:111], v[22:23], off offset:256
	global_load_dwordx4 v[112:115], v[20:21], off offset:256
	global_load_dwordx4 v[116:119], v[22:23], off offset:288
	global_load_dwordx4 v[120:123], v[20:21], off offset:288
	global_load_dwordx4 v[124:127], v[22:23], off offset:320
	global_load_dwordx4 v[128:131], v[20:21], off offset:320
	v_lshlrev_b32_e32 v178, 2, v40
	s_add_i32 s1, s1, s87
	s_add_i32 s0, s0, s7
	s_cmpk_lt_i32 s1, 0x100
	s_waitcnt vmcnt(20)
	v_mfma_f32_32x32x16_bf16 v[0:15], v[44:47], v[48:51], 0
	global_load_dwordx4 v[44:47], v[22:23], off offset:352
	global_load_dwordx4 v[48:51], v[20:21], off offset:352
	s_waitcnt vmcnt(20)
	v_mfma_f32_32x32x16_bf16 v[0:15], v[52:55], v[56:59], v[0:15]
	global_load_dwordx4 v[52:55], v[22:23], off offset:384
	global_load_dwordx4 v[56:59], v[20:21], off offset:384
	s_waitcnt vmcnt(20)
	v_mfma_f32_32x32x16_bf16 v[0:15], v[60:63], v[64:67], v[0:15]
	global_load_dwordx4 v[60:63], v[22:23], off offset:416
	global_load_dwordx4 v[64:67], v[20:21], off offset:416
	s_waitcnt vmcnt(20)
	v_mfma_f32_32x32x16_bf16 v[0:15], v[68:71], v[72:75], v[0:15]
	global_load_dwordx4 v[68:71], v[22:23], off offset:448
	global_load_dwordx4 v[72:75], v[20:21], off offset:448
	s_waitcnt vmcnt(20)
	v_mfma_f32_32x32x16_bf16 v[0:15], v[76:79], v[80:83], v[0:15]
	global_load_dwordx4 v[76:79], v[22:23], off offset:480
	global_load_dwordx4 v[80:83], v[20:21], off offset:480
	s_waitcnt vmcnt(20)
	v_mfma_f32_32x32x16_bf16 v[0:15], v[84:87], v[88:91], v[0:15]
	global_load_dwordx4 v[84:87], v[22:23], off offset:512
	global_load_dwordx4 v[88:91], v[20:21], off offset:512
	s_waitcnt vmcnt(20)
	v_mfma_f32_32x32x16_bf16 v[0:15], v[92:95], v[96:99], v[0:15]
	global_load_dwordx4 v[92:95], v[22:23], off offset:544
	global_load_dwordx4 v[96:99], v[20:21], off offset:544
	s_waitcnt vmcnt(20)
	v_mfma_f32_32x32x16_bf16 v[0:15], v[100:103], v[104:107], v[0:15]
	global_load_dwordx4 v[100:103], v[22:23], off offset:576
	global_load_dwordx4 v[104:107], v[20:21], off offset:576
	s_waitcnt vmcnt(20)
	v_mfma_f32_32x32x16_bf16 v[0:15], v[108:111], v[112:115], v[0:15]
	global_load_dwordx4 v[108:111], v[22:23], off offset:608
	global_load_dwordx4 v[112:115], v[20:21], off offset:608
	s_waitcnt vmcnt(20)
	v_mfma_f32_32x32x16_bf16 v[0:15], v[116:119], v[120:123], v[0:15]
	global_load_dwordx4 v[116:119], v[22:23], off offset:640
	global_load_dwordx4 v[120:123], v[20:21], off offset:640
	s_waitcnt vmcnt(20)
	v_mfma_f32_32x32x16_bf16 v[0:15], v[124:127], v[128:131], v[0:15]
	global_load_dwordx4 v[124:127], v[22:23], off offset:672
	global_load_dwordx4 v[128:131], v[20:21], off offset:672
	s_waitcnt vmcnt(20)
	v_mfma_f32_32x32x16_bf16 v[0:15], v[44:47], v[48:51], v[0:15]
	s_waitcnt vmcnt(18)
	v_mfma_f32_32x32x16_bf16 v[0:15], v[52:55], v[56:59], v[0:15]
	s_waitcnt vmcnt(16)
	v_mfma_f32_32x32x16_bf16 v[0:15], v[60:63], v[64:67], v[0:15]
	s_waitcnt vmcnt(14)
	v_mfma_f32_32x32x16_bf16 v[0:15], v[68:71], v[72:75], v[0:15]
	s_waitcnt vmcnt(12)
	v_mfma_f32_32x32x16_bf16 v[0:15], v[76:79], v[80:83], v[0:15]
	s_waitcnt vmcnt(10)
	v_mfma_f32_32x32x16_bf16 v[0:15], v[84:87], v[88:91], v[0:15]
	s_waitcnt vmcnt(8)
	v_mfma_f32_32x32x16_bf16 v[0:15], v[92:95], v[96:99], v[0:15]
	s_waitcnt vmcnt(6)
	v_mfma_f32_32x32x16_bf16 v[0:15], v[100:103], v[104:107], v[0:15]
	s_waitcnt vmcnt(4)
	v_mfma_f32_32x32x16_bf16 v[0:15], v[108:111], v[112:115], v[0:15]
	s_waitcnt vmcnt(2)
	v_mfma_f32_32x32x16_bf16 v[0:15], v[116:119], v[120:123], v[0:15]
	s_barrier
; DI int crow(int i, int h) { return (i & 3) + 8 * (i >> 2) + 4 * h; }
; DI float micro_sum(const float* red, int i, int lane) {
;   float s = 0.f;
; #pragma unroll
;   for (int q = 0; q < 8; ++q) s += red[(q * 16 + i) * 64 + lane];
;   return s;
; }
; DI void phase_res(const Params& p, int l, int mode, unsigned char* smem) {
;     ...
;       __syncthreads();
;       micro_reduce_store(pa, red, w, lane);
;       __syncthreads();
; #pragma unroll
;       for (int q = 0; q < 2; ++q) {
;         const int i = w + 8 * q;
;         const float sa = micro_sum(red, i, lane);
;         const int row = row0 + crow(i, h), n = n0 + r;
;         const float gg = mod[((size_t)l * 40 + batch_of_row(row)) * 6144 + gi * 1024 + n];
;         float* xr = p.out + (size_t)row * 1024 + n;
;         float xv = (mode == 0 && l == 0) ? p.in[1][(size_t)(row - TOKP) * 1024 + n] : *xr;
;         if (!(mode == 0 && l == 0)) {
;           const float2 st = *(const float2*)(stats + (size_t)row * 2);
;           xv = (xv - st.x) * st.y * rlg[n] + rlb[n];
;         }
;         *xr = ALPHA * xv + (1.f + gg) * sa;
;       }
	s_waitcnt vmcnt(0)
	v_mfma_f32_32x32x16_bf16 v[0:15], v[124:127], v[128:131], v[0:15]
	s_nop 11
	ds_write2_b32 v31, v0, v1 offset0:16 offset1:80
	ds_write2_b32 v31, v2, v3 offset0:144 offset1:208
	v_add_u32_e32 v0, 64, v31
	ds_write2st64_b32 v0, v4, v5 offset0:4 offset1:5
	ds_write2st64_b32 v0, v6, v7 offset0:6 offset1:7
	ds_write2st64_b32 v0, v8, v9 offset0:8 offset1:9
	ds_write2st64_b32 v0, v10, v11 offset0:10 offset1:11
	ds_write2st64_b32 v0, v12, v13 offset0:12 offset1:13
	ds_write2st64_b32 v0, v14, v15 offset0:14 offset1:15
	v_add_u32_e32 v6, 64, v25
	s_waitcnt lgkmcnt(0)
	s_barrier
	ds_read2st64_b32 v[4:5], v6 offset1:16
	v_lshl_add_u64 v[2:3], s[8:9], 0, v[178:179]
	v_lshl_add_u64 v[0:1], s[48:49], 0, v[178:179]
	s_waitcnt lgkmcnt(0)
	v_add_f32_e32 v4, 0, v4
	v_add_f32_e32 v7, v4, v5
	ds_read2st64_b32 v[4:5], v6 offset0:32 offset1:48
	s_waitcnt lgkmcnt(0)
	v_add_f32_e32 v4, v7, v4
	v_add_f32_e32 v7, v4, v5
	ds_read2st64_b32 v[4:5], v6 offset0:64 offset1:80
	s_waitcnt lgkmcnt(0)
	v_add_f32_e32 v4, v7, v4
	v_add_f32_e32 v7, v4, v5
	ds_read2st64_b32 v[4:5], v6 offset0:96 offset1:112
	v_add_u32_e32 v6, s2, v26
	v_lshrrev_b32_e32 v6, 5, v6
	v_add_u32_e32 v6, 32, v6
	s_waitcnt lgkmcnt(0)
	v_add_f32_e32 v4, v7, v4
	v_add_f32_e32 v10, v4, v5
	v_add_u32_e32 v4, s3, v27
	v_cmp_gt_i32_e32 vcc, s33, v4
	v_ashrrev_i32_e32 v5, 11, v4
	s_nop 0
	v_cndmask_b32_e32 v6, v6, v5, vcc
	v_ashrrev_i32_e32 v7, 31, v6
	v_lshl_add_u64 v[6:7], v[6:7], 0, s[14:15]
	v_mad_u64_u32 v[8:9], s[4:5], v6, s86, v[2:3]
	v_ashrrev_i32_e32 v5, 31, v4
	v_mad_i32_i24 v9, v7, s86, v9
	v_lshlrev_b64 v[6:7], 12, v[4:5]
	v_lshl_add_u64 v[6:7], v[0:1], 0, v[6:7]
	v_lshl_add_u64 v[4:5], v[4:5], 3, s[80:81]
	global_load_dword v8, v[8:9], off
	s_nop 0
	global_load_dword v9, v[6:7], off
	s_nop 0
	global_load_dwordx2 v[4:5], v[4:5], off
	s_waitcnt vmcnt(0)
	v_sub_f32_e32 v4, v9, v4
	v_mul_f32_e32 v4, v4, v5
	global_load_dword v5, v178, s[16:17]
	global_load_dword v9, v178, s[18:19]
	s_waitcnt vmcnt(0)
	v_fmac_f32_e32 v9, v4, v5
	v_mul_f32_e32 v4, 0x3fb504f3, v9
	v_add_f32_e32 v5, 1.0, v8
	v_fmac_f32_e32 v4, v10, v5
	global_store_dword v[6:7], v4, off
	v_add_u32_e32 v6, 64, v28
	ds_read2st64_b32 v[4:5], v6 offset1:16
	s_waitcnt lgkmcnt(0)
	v_add_f32_e32 v4, 0, v4
	v_add_f32_e32 v7, v4, v5
	ds_read2st64_b32 v[4:5], v6 offset0:32 offset1:48
	s_waitcnt lgkmcnt(0)
	v_add_f32_e32 v4, v7, v4
	v_add_f32_e32 v7, v4, v5
	ds_read2st64_b32 v[4:5], v6 offset0:64 offset1:80
	s_waitcnt lgkmcnt(0)
	v_add_f32_e32 v4, v7, v4
	v_add_f32_e32 v7, v4, v5
	ds_read2st64_b32 v[4:5], v6 offset0:96 offset1:112
	v_add_u32_e32 v6, s2, v29
	v_lshrrev_b32_e32 v6, 5, v6
	v_add_u32_e32 v6, 32, v6
	s_waitcnt lgkmcnt(0)
	v_add_f32_e32 v4, v7, v4
	v_add_f32_e32 v8, v4, v5
	v_add_u32_e32 v4, s3, v30
	v_cmp_gt_i32_e32 vcc, s33, v4
	v_ashrrev_i32_e32 v5, 11, v4
	s_nop 0
	v_cndmask_b32_e32 v6, v6, v5, vcc
	v_ashrrev_i32_e32 v7, 31, v6
	v_lshl_add_u64 v[6:7], v[6:7], 0, s[14:15]
	v_mad_u64_u32 v[2:3], s[2:3], v6, s86, v[2:3]
	v_mad_i32_i24 v3, v7, s86, v3
	v_ashrrev_i32_e32 v5, 31, v4
	global_load_dword v6, v[2:3], off
	v_lshlrev_b64 v[2:3], 12, v[4:5]
	v_lshl_add_u64 v[0:1], v[0:1], 0, v[2:3]
	v_lshl_add_u64 v[2:3], v[4:5], 3, s[80:81]
	global_load_dword v7, v[0:1], off
	s_nop 0
	global_load_dwordx2 v[2:3], v[2:3], off
	s_waitcnt vmcnt(0)
	v_sub_f32_e32 v2, v7, v2
	v_mul_f32_e32 v2, v2, v3
	global_load_dword v3, v178, s[16:17]
	global_load_dword v4, v178, s[18:19]
	s_waitcnt vmcnt(0)
	v_fmac_f32_e32 v4, v2, v3
	v_mul_f32_e32 v2, 0x3fb504f3, v4
	v_add_f32_e32 v3, 1.0, v6
	v_fmac_f32_e32 v2, v8, v3
	global_store_dword v[0:1], v2, off
	s_cbranch_scc1 .LBB0_883
